# phase_taps f32-MFMA sections: hidden-layer rows fetched through a 16-slot register ring with counted vmcnt waits instead of one load + vmcnt(0) per 4 MFMAs (on top of the pipelined GEMM2 hook)
# speedup vs baseline: 1.0093x; 1.0002x over previous
.LBB0_227:
	s_or_b64 exec, exec, s[0:1]
	v_cmp_gt_i32_e32 vcc, 16, v82
	s_and_saveexec_b64 s[0:1], vcc
	v_lshl_add_u32 v1, v82, 10, 0
	ds_write_b16 v1, v0 offset:16384
	s_or_b64 exec, exec, s[0:1]
	s_movk_i32 s0, 0x80
	v_cmp_gt_i32_e32 vcc, s0, v82
	s_and_saveexec_b64 s[0:1], vcc
	v_lshl_add_u32 v1, v82, 2, 0
	ds_write_b32 v1, v0 offset:8192
	s_or_b64 exec, exec, s[0:1]
	v_lshlrev_b32_e32 v2, 2, v82
	v_and_b32_e32 v16, 0xc0, v2
	v_ashrrev_i32_e32 v2, 1, v82
	v_and_b32_e32 v54, 0xffffffc0, v2
	s_lshl_b32 s0, s9, 20
	v_readlane_b32 s2, v253, 31
	v_and_b32_e32 v1, 15, v82
	v_or_b32_e32 v56, 16, v54
	v_readlane_b32 s3, v253, 32
	s_add_u32 s0, s2, s0
	v_or_b32_e32 v2, v54, v1
	v_or_b32_e32 v6, v56, v1
	s_addc_u32 s1, s3, 0
	v_mov_b32_e32 v17, v0
	v_ashrrev_i32_e32 v3, 31, v2
	v_ashrrev_i32_e32 v7, 31, v6
	v_lshl_add_u64 v[44:45], s[0:1], 0, v[16:17]
	v_lshlrev_b64 v[2:3], 8, v[2:3]
	v_lshlrev_b64 v[6:7], 8, v[6:7]
	v_lshl_add_u64 v[36:37], v[44:45], 0, v[2:3]
	v_lshl_add_u64 v[40:41], v[44:45], 0, v[6:7]
	s_waitcnt lgkmcnt(0)
	s_barrier
	v_mov_b64_e32 v[142:143], v[36:37]
	v_mov_b64_e32 v[238:239], v[142:143]
	global_load_dwordx4 v[144:147], v[238:239], off
	s_mov_b64 s[100:101], 0x1000
	v_lshl_add_u64 v[238:239], v[142:143], 0, s[100:101]
	global_load_dwordx4 v[148:151], v[238:239], off
	v_mov_b64_e32 v[238:239], v[142:143]
	global_load_dwordx4 v[152:155], v[238:239], off offset:16
	s_mov_b64 s[100:101], 0x1000
	v_lshl_add_u64 v[238:239], v[142:143], 0, s[100:101]
	global_load_dwordx4 v[156:159], v[238:239], off offset:16
	s_mov_b64 s[100:101], 0x1000
	v_lshl_add_u64 v[238:239], v[142:143], 0, s[100:101]
	global_load_dwordx4 v[160:163], v[238:239], off offset:32
	v_mov_b64_e32 v[238:239], v[142:143]
	global_load_dwordx4 v[164:167], v[238:239], off offset:32
	s_mov_b64 s[100:101], 0x1000
	v_lshl_add_u64 v[238:239], v[142:143], 0, s[100:101]
	global_load_dwordx4 v[168:171], v[238:239], off offset:48
	v_mov_b64_e32 v[238:239], v[142:143]
	global_load_dwordx4 v[172:175], v[238:239], off offset:48
	s_mov_b64 s[100:101], 0x2000
	v_lshl_add_u64 v[238:239], v[142:143], 0, s[100:101]
	global_load_dwordx4 v[176:179], v[238:239], off
	s_mov_b64 s[100:101], 0x2000
	v_lshl_add_u64 v[238:239], v[142:143], 0, s[100:101]
	global_load_dwordx4 v[180:183], v[238:239], off offset:16
	s_mov_b64 s[100:101], 0x2000
	v_lshl_add_u64 v[238:239], v[142:143], 0, s[100:101]
	global_load_dwordx4 v[184:187], v[238:239], off offset:32
	s_mov_b64 s[100:101], 0x2000
	v_lshl_add_u64 v[238:239], v[142:143], 0, s[100:101]
	global_load_dwordx4 v[188:191], v[238:239], off offset:48
	s_mov_b64 s[100:101], 0x3000
	v_lshl_add_u64 v[238:239], v[142:143], 0, s[100:101]
	global_load_dwordx4 v[192:195], v[238:239], off
	s_mov_b64 s[100:101], 0x3000
	v_lshl_add_u64 v[238:239], v[142:143], 0, s[100:101]
	global_load_dwordx4 v[204:207], v[238:239], off offset:16
	s_mov_b64 s[100:101], 0x3000
	v_lshl_add_u64 v[238:239], v[142:143], 0, s[100:101]
	global_load_dwordx4 v[208:211], v[238:239], off offset:32
	s_mov_b64 s[100:101], 0x3000
	v_lshl_add_u64 v[238:239], v[142:143], 0, s[100:101]
	global_load_dwordx4 v[212:215], v[238:239], off offset:48
	v_lshrrev_b32_e32 v55, 2, v82
	v_and_b32_e32 v6, 16, v55
	v_or_b32_e32 v7, v6, v1
	v_lshlrev_b32_e32 v17, 8, v7
	v_add3_u32 v38, 0, v17, v16
	ds_read_b128 v[16:19], v38
	ds_read_b128 v[20:23], v38 offset:16
	v_or_b32_e32 v57, 32, v54
	v_or_b32_e32 v58, 48, v54
	s_lshl_b32 s2, s11, 4
	v_and_b32_e32 v59, 12, v55
	v_cmp_lt_i32_e32 vcc, v234, v229
	s_waitcnt lgkmcnt(0)
	s_waitcnt vmcnt(15)
	v_mfma_f32_16x16x4_f32 v[24:27], v144, v16, 0
	s_waitcnt vmcnt(14)
	v_mfma_f32_16x16x4_f32 v[32:35], v148, v16, 0
	v_mfma_f32_16x16x4_f32 v[24:27], v145, v17, v[24:27]
	v_mfma_f32_16x16x4_f32 v[32:35], v149, v17, v[32:35]
	v_mfma_f32_16x16x4_f32 v[24:27], v146, v18, v[24:27]
	v_mfma_f32_16x16x4_f32 v[32:35], v150, v18, v[32:35]
	v_mfma_f32_16x16x4_f32 v[2:5], v147, v19, v[24:27]
	s_nop 7
	v_mfma_f32_16x16x4_f32 v[8:11], v151, v19, v[32:35]
	s_waitcnt vmcnt(13)
	v_mfma_f32_16x16x4_f32 v[2:5], v152, v20, v[2:5]
	s_waitcnt vmcnt(12)
	v_mfma_f32_16x16x4_f32 v[8:11], v156, v20, v[8:11]
	v_mfma_f32_16x16x4_f32 v[2:5], v153, v21, v[2:5]
	v_mfma_f32_16x16x4_f32 v[8:11], v157, v21, v[8:11]
	v_mfma_f32_16x16x4_f32 v[2:5], v154, v22, v[2:5]
	v_mfma_f32_16x16x4_f32 v[8:11], v158, v22, v[8:11]
	v_mfma_f32_16x16x4_f32 v[12:15], v155, v23, v[2:5]
	v_mfma_f32_16x16x4_f32 v[8:11], v159, v23, v[8:11]
	ds_read_b128 v[28:31], v38 offset:32
	s_nop 5
	ds_read_b128 v[2:5], v38 offset:48
	s_nop 0
	s_nop 0
	s_waitcnt lgkmcnt(1)
	s_waitcnt vmcnt(11)
	v_mfma_f32_16x16x4_f32 v[8:11], v160, v28, v[8:11]
	v_mfma_f32_16x16x4_f32 v[8:11], v161, v29, v[8:11]
	v_mfma_f32_16x16x4_f32 v[8:11], v162, v30, v[8:11]
	s_waitcnt vmcnt(10)
	v_mfma_f32_16x16x4_f32 v[12:15], v164, v28, v[12:15]
	v_or_b32_e32 v24, v57, v1
	v_mfma_f32_16x16x4_f32 v[8:11], v163, v31, v[8:11]
	v_mfma_f32_16x16x4_f32 v[12:15], v165, v29, v[12:15]
	v_ashrrev_i32_e32 v25, 31, v24
	v_lshlrev_b64 v[24:25], 8, v[24:25]
	s_waitcnt lgkmcnt(0)
	s_waitcnt vmcnt(9)
	v_mfma_f32_16x16x4_f32 v[8:11], v168, v2, v[8:11]
	v_mfma_f32_16x16x4_f32 v[12:15], v166, v30, v[12:15]
	v_mfma_f32_16x16x4_f32 v[8:11], v169, v3, v[8:11]
	v_lshl_add_u64 v[40:41], v[44:45], 0, v[24:25]
	v_mfma_f32_16x16x4_f32 v[12:15], v167, v31, v[12:15]
	s_waitcnt vmcnt(8)
	v_mfma_f32_16x16x4_f32 v[12:15], v172, v2, v[12:15]
	v_mfma_f32_16x16x4_f32 v[12:15], v173, v3, v[12:15]
	v_mfma_f32_16x16x4_f32 v[12:15], v174, v4, v[12:15]
	v_mfma_f32_16x16x4_f32 v[8:11], v170, v4, v[8:11]
	v_mfma_f32_16x16x4_f32 v[12:15], v175, v5, v[12:15]
	v_mfma_f32_16x16x4_f32 v[32:35], v171, v5, v[8:11]
	s_nop 7
	s_waitcnt vmcnt(7)
	v_mfma_f32_16x16x4_f32 v[36:39], v176, v16, 0
	v_mfma_f32_16x16x4_f32 v[36:39], v177, v17, v[36:39]
	v_mfma_f32_16x16x4_f32 v[36:39], v178, v18, v[36:39]
	v_mfma_f32_16x16x4_f32 v[24:27], v179, v19, v[36:39]
	s_nop 8
	s_waitcnt vmcnt(6)
	v_mfma_f32_16x16x4_f32 v[24:27], v180, v20, v[24:27]
	v_mfma_f32_16x16x4_f32 v[24:27], v181, v21, v[24:27]
	v_mfma_f32_16x16x4_f32 v[24:27], v182, v22, v[24:27]
	v_mfma_f32_16x16x4_f32 v[8:11], v183, v23, v[24:27]
	s_nop 8
	s_waitcnt vmcnt(5)
	v_mfma_f32_16x16x4_f32 v[8:11], v184, v28, v[8:11]
	v_or_b32_e32 v36, v58, v1
	v_mfma_f32_16x16x4_f32 v[8:11], v185, v29, v[8:11]
	v_ashrrev_i32_e32 v37, 31, v36
	v_lshlrev_b64 v[36:37], 8, v[36:37]
	v_lshl_add_u64 v[52:53], v[44:45], 0, v[36:37]
	v_mfma_f32_16x16x4_f32 v[8:11], v186, v30, v[8:11]
	v_mfma_f32_16x16x4_f32 v[8:11], v187, v31, v[8:11]
	s_waitcnt vmcnt(4)
	v_mfma_f32_16x16x4_f32 v[8:11], v188, v2, v[8:11]
	v_mfma_f32_16x16x4_f32 v[8:11], v189, v3, v[8:11]
	v_mfma_f32_16x16x4_f32 v[44:47], v190, v4, v[8:11]
	s_nop 8
	v_or_b32_e32 v8, s2, v1
	v_cvt_f32_u32_e32 v9, v8
	v_or_b32_e32 v8, v54, v59
	v_cvt_f32_i32_e32 v10, v8
	v_fmamk_f32 v60, v9, 0xbcc4df2d, v222
	v_mul_f32_e32 v9, 0xbb808081, v10
	v_mfma_f32_16x16x4_f32 v[44:47], v191, v5, v[44:47]
	v_mul_f32_e64 v9, v9, |v60|
	v_mul_f32_e32 v9, 0x3fb8aa3b, v9
	v_exp_f32_e32 v10, v9
	v_or_b32_e32 v9, 1, v8
	v_cvt_f32_i32_e32 v11, v9
	v_mul_f32_e32 v12, v10, v12
	s_waitcnt vmcnt(3)
	v_mfma_f32_16x16x4_f32 v[24:27], v192, v16, 0
	v_or_b32_e32 v10, 2, v8
	v_cvt_f32_i32_e32 v16, v10
	v_mul_f32_e32 v11, 0xbb808081, v11
	v_mul_f32_e64 v11, v11, |v60|
	v_mul_f32_e32 v11, 0x3fb8aa3b, v11
	v_mfma_f32_16x16x4_f32 v[24:27], v193, v17, v[24:27]
	v_exp_f32_e32 v17, v11
	v_mul_f32_e32 v11, 0xbb808081, v16
	v_mul_f32_e64 v11, v11, |v60|
	v_mul_f32_e32 v11, 0x3fb8aa3b, v11
	v_exp_f32_e32 v16, v11
	v_or_b32_e32 v11, 3, v8
	v_cvt_f32_i32_e32 v36, v11
	v_mfma_f32_16x16x4_f32 v[24:27], v194, v18, v[24:27]
	v_mul_f32_e32 v18, v17, v13
	v_mul_f32_e32 v14, v16, v14
	v_mul_f32_e32 v16, 0xbb808081, v36
	v_add_f32_e64 v13, |v12|, |v18|
	v_mul_f32_e64 v16, v16, |v60|
	v_mul_f32_e32 v16, 0x3fb8aa3b, v16
	v_add_f32_e64 v17, |v14|, v13
	v_mfma_f32_16x16x4_f32 v[24:27], v195, v19, v[24:27]
	v_or_b32_e32 v13, v56, v59
	v_exp_f32_e32 v16, v16
	v_cvt_f32_i32_e32 v19, v13
	v_mul_f32_e32 v16, v16, v15
	v_mul_f32_e32 v15, 0xbb808081, v19
	s_waitcnt vmcnt(2)
	v_mfma_f32_16x16x4_f32 v[24:27], v204, v20, v[24:27]
	v_mul_f32_e64 v15, v15, |v60|
	v_mul_f32_e32 v15, 0x3fb8aa3b, v15
	v_exp_f32_e32 v19, v15
	v_or_b32_e32 v15, 1, v13
	v_cvt_f32_i32_e32 v36, v15
	v_add_f32_e64 v17, |v16|, v17
	v_mul_f32_e32 v20, v19, v32
	v_mfma_f32_16x16x4_f32 v[24:27], v205, v21, v[24:27]
	v_add_f32_e64 v21, v17, |v20|
	v_mul_f32_e32 v17, 0xbb808081, v36
	v_mul_f32_e64 v19, |v60|, v17
	v_or_b32_e32 v17, 2, v13
	v_cvt_f32_i32_e32 v32, v17
	v_mul_f32_e32 v19, 0x3fb8aa3b, v19
	v_mfma_f32_16x16x4_f32 v[24:27], v206, v22, v[24:27]
	v_exp_f32_e32 v22, v19
	v_mul_f32_e32 v19, 0xbb808081, v32
	v_mul_f32_e64 v19, |v60|, v19
	v_mul_f32_e32 v19, 0x3fb8aa3b, v19
	v_exp_f32_e32 v32, v19
	v_or_b32_e32 v19, 3, v13
	v_cvt_f32_i32_e32 v40, v19
	v_mfma_f32_16x16x4_f32 v[36:39], v207, v23, v[24:27]
	s_nop 1
	v_mul_f32_e32 v25, v22, v33
	v_add_f32_e64 v22, |v25|, v21
	v_mul_f32_e32 v21, 0xbb808081, v40
	v_mul_f32_e64 v21, |v60|, v21
	v_mul_f32_e32 v21, 0x3fb8aa3b, v21
	v_exp_f32_e32 v24, v21
	v_or_b32_e32 v21, v57, v59
	s_waitcnt vmcnt(1)
	v_mfma_f32_16x16x4_f32 v[36:39], v208, v28, v[36:39]
	v_cvt_f32_i32_e32 v26, v21
	v_mul_f32_e32 v23, v32, v34
	v_add_f32_e64 v22, |v23|, v22
	v_mul_f32_e32 v24, v24, v35
	v_mul_f32_e32 v32, 0xbb808081, v26
	v_add_f32_e64 v40, |v24|, v22
	v_or_b32_e32 v22, 1, v21
	v_mfma_f32_16x16x4_f32 v[26:29], v209, v29, v[36:39]
	v_cvt_f32_i32_e32 v33, v22
	v_mul_f32_e64 v32, v32, |v60|
	v_mul_f32_e32 v32, 0x3fb8aa3b, v32
	v_exp_f32_e32 v36, v32
	v_mul_f32_e32 v32, 0xbb808081, v33
	v_mul_f32_e64 v32, |v60|, v32
	v_mul_f32_e32 v37, 0x3fb8aa3b, v32
	v_mfma_f32_16x16x4_f32 v[32:35], v210, v30, v[26:29]
	s_nop 1
	v_or_b32_e32 v26, 2, v21
	v_exp_f32_e32 v27, v37
	v_cvt_f32_i32_e32 v29, v26
	v_mul_f32_e32 v30, v36, v44
	v_add_f32_e64 v36, v40, |v30|
	v_mul_f32_e32 v28, v27, v45
	v_mul_f32_e32 v27, 0xbb808081, v29
	v_mfma_f32_16x16x4_f32 v[32:35], v211, v31, v[32:35]
	v_mul_f32_e64 v27, |v60|, v27
	v_mul_f32_e32 v27, 0x3fb8aa3b, v27
	v_exp_f32_e32 v29, v27
	v_or_b32_e32 v27, 3, v21
	v_add_f32_e64 v31, |v28|, v36
	v_cvt_f32_i32_e32 v36, v27
	v_mul_f32_e32 v29, v29, v46
	s_waitcnt vmcnt(0)
	v_mfma_f32_16x16x4_f32 v[32:35], v212, v2, v[32:35]
	v_add_f32_e64 v37, |v29|, v31
	v_mul_f32_e32 v2, 0xbb808081, v36
	v_mul_f32_e64 v2, |v60|, v2
	v_mul_f32_e32 v2, 0x3fb8aa3b, v2
	v_exp_f32_e32 v31, v2
	v_or_b32_e32 v2, v58, v59
	v_cvt_f32_i32_e32 v36, v2
	v_mfma_f32_16x16x4_f32 v[32:35], v213, v3, v[32:35]
	v_mul_f32_e32 v31, v31, v47
	v_add_f32_e64 v38, |v31|, v37
	v_mul_f32_e32 v3, 0xbb808081, v36
	v_mul_f32_e64 v36, v3, |v60|
	v_or_b32_e32 v3, 1, v2
	v_cvt_f32_i32_e32 v37, v3
	v_mul_f32_e32 v36, 0x3fb8aa3b, v36
	v_mfma_f32_16x16x4_f32 v[32:35], v214, v4, v[32:35]
	v_exp_f32_e32 v39, v36
	v_mul_f32_e32 v4, 0xbb808081, v37
	v_mul_f32_e64 v4, |v60|, v4
	v_mul_f32_e32 v4, 0x3fb8aa3b, v4
	v_exp_f32_e32 v40, v4
	v_or_b32_e32 v4, 2, v2
	v_cvt_f32_i32_e32 v41, v4
	v_mfma_f32_16x16x4_f32 v[34:37], v215, v5, v[32:35]
	v_or_b32_e32 v5, 3, v2
	s_nop 8
	v_mul_f32_e32 v33, v39, v34
	v_add_f32_e64 v34, v38, |v33|
	v_cvt_f32_i32_e32 v38, v5
	v_mul_f32_e32 v32, v40, v35
	v_mul_f32_e32 v35, 0xbb808081, v41
	v_mul_f32_e64 v35, |v60|, v35
	v_mul_f32_e32 v38, 0xbb808081, v38
	v_mul_f32_e32 v35, 0x3fb8aa3b, v35
	v_mul_f32_e64 v38, |v60|, v38
	v_exp_f32_e32 v35, v35
	v_mul_f32_e32 v38, 0x3fb8aa3b, v38
	v_exp_f32_e32 v38, v38
	v_add_f32_e64 v34, |v32|, v34
	v_mul_f32_e32 v35, v35, v36
	v_add_f32_e64 v36, |v35|, v34
	v_mul_f32_e32 v34, v38, v37
	v_cndmask_b32_e32 v37, v228, v234, vcc
	v_add_f32_e64 v36, |v34|, v36
	v_lshlrev_b32_e32 v37, 2, v37
	ds_bpermute_b32 v37, v37, v36
	v_cmp_lt_i32_e32 vcc, v235, v229
	s_waitcnt lgkmcnt(0)
	v_add_f32_e32 v36, v36, v37
	v_cndmask_b32_e32 v37, v228, v235, vcc
	v_lshlrev_b32_e32 v37, 2, v37
	ds_bpermute_b32 v38, v37, v36
	v_and_b32_e32 v37, 63, v82
	v_cmp_gt_u32_e32 vcc, 16, v37
	s_and_saveexec_b64 s[0:1], vcc
	s_cbranch_execz .LBB0_233
	s_waitcnt lgkmcnt(0)
	v_add_f32_e32 v36, v36, v38
	v_and_b32_e32 v38, 0xffffffc0, v82
	v_lshlrev_b32_e32 v37, 2, v37
	v_add3_u32 v37, 0, v38, v37
	ds_write_b32 v37, v36 offset:8192

.LBB0_249:
	s_or_b64 exec, exec, s[0:1]
	v_cmp_gt_i32_e32 vcc, 8, v82
	s_and_saveexec_b64 s[0:1], vcc
	v_lshl_add_u32 v1, v82, 13, 0
	ds_write_b16 v1, v0 offset:16384
	s_or_b64 exec, exec, s[0:1]
	s_movk_i32 s0, 0x80
	v_cmp_gt_i32_e32 vcc, s0, v82
	v_lshl_add_u32 v1, v82, 2, 0
	s_and_saveexec_b64 s[0:1], vcc
	ds_write_b32 v1, v0 offset:8192
	s_or_b64 exec, exec, s[0:1]
	s_lshl_b32 s0, s9, 20
	v_ashrrev_i32_e32 v64, 2, v82
	s_add_u32 s0, s14, s0
	v_and_b32_e32 v88, -16, v64
	v_lshlrev_b32_e32 v2, 2, v82
	s_addc_u32 s1, s15, 0
	v_and_b32_e32 v83, 15, v82
	v_and_b32_e32 v6, 0xc0, v2
	v_mov_b32_e32 v7, v0
	v_lshlrev_b32_e32 v91, 4, v88
	v_lshl_add_u64 v[2:3], s[0:1], 0, v[6:7]
	s_mov_b64 s[0:1], 0x280000
	v_lshlrev_b32_e32 v7, 8, v83
	v_or_b32_e32 v92, 16, v91
	v_lshl_add_u64 v[62:63], v[2:3], 0, s[0:1]
	v_or_b32_e32 v2, v91, v83
	v_add3_u32 v18, 0, v7, v6
	v_or_b32_e32 v6, v92, v83
	v_ashrrev_i32_e32 v3, 31, v2
	v_ashrrev_i32_e32 v7, 31, v6
	v_lshlrev_b64 v[2:3], 8, v[2:3]
	v_lshlrev_b64 v[6:7], 8, v[6:7]
	v_lshl_add_u64 v[22:23], v[62:63], 0, v[2:3]
	v_lshl_add_u64 v[24:25], v[62:63], 0, v[6:7]
	s_waitcnt lgkmcnt(0)
	s_barrier
	v_mov_b64_e32 v[142:143], v[22:23]
	v_mov_b64_e32 v[238:239], v[142:143]
	global_load_dwordx4 v[144:147], v[238:239], off
	s_mov_b64 s[100:101], 0x1000
	v_lshl_add_u64 v[238:239], v[142:143], 0, s[100:101]
	global_load_dwordx4 v[148:151], v[238:239], off
	s_mov_b64 s[100:101], 0x1000
	v_lshl_add_u64 v[238:239], v[142:143], 0, s[100:101]
	global_load_dwordx4 v[152:155], v[238:239], off offset:16
	v_mov_b64_e32 v[238:239], v[142:143]
	global_load_dwordx4 v[156:159], v[238:239], off offset:16
	v_mov_b64_e32 v[238:239], v[142:143]
	global_load_dwordx4 v[160:163], v[238:239], off offset:32
	s_mov_b64 s[100:101], 0x1000
	v_lshl_add_u64 v[238:239], v[142:143], 0, s[100:101]
	global_load_dwordx4 v[164:167], v[238:239], off offset:32
	v_mov_b64_e32 v[238:239], v[142:143]
	global_load_dwordx4 v[168:171], v[238:239], off offset:48
	s_mov_b64 s[100:101], 0x1000
	v_lshl_add_u64 v[238:239], v[142:143], 0, s[100:101]
	global_load_dwordx4 v[172:175], v[238:239], off offset:48
	s_mov_b64 s[100:101], 0x2000
	v_lshl_add_u64 v[238:239], v[142:143], 0, s[100:101]
	global_load_dwordx4 v[176:179], v[238:239], off
	s_mov_b64 s[100:101], 0x2000
	v_lshl_add_u64 v[238:239], v[142:143], 0, s[100:101]
	global_load_dwordx4 v[180:183], v[238:239], off offset:16
	s_mov_b64 s[100:101], 0x2000
	v_lshl_add_u64 v[238:239], v[142:143], 0, s[100:101]
	global_load_dwordx4 v[184:187], v[238:239], off offset:32
	s_mov_b64 s[100:101], 0x2000
	v_lshl_add_u64 v[238:239], v[142:143], 0, s[100:101]
	global_load_dwordx4 v[188:191], v[238:239], off offset:48
	s_mov_b64 s[100:101], 0x3000
	v_lshl_add_u64 v[238:239], v[142:143], 0, s[100:101]
	global_load_dwordx4 v[192:195], v[238:239], off
	s_mov_b64 s[100:101], 0x3000
	v_lshl_add_u64 v[238:239], v[142:143], 0, s[100:101]
	global_load_dwordx4 v[204:207], v[238:239], off offset:16
	s_mov_b64 s[100:101], 0x3000
	v_lshl_add_u64 v[238:239], v[142:143], 0, s[100:101]
	global_load_dwordx4 v[208:211], v[238:239], off offset:32
	s_mov_b64 s[100:101], 0x3000
	v_lshl_add_u64 v[238:239], v[142:143], 0, s[100:101]
	global_load_dwordx4 v[212:215], v[238:239], off offset:48
	ds_read_b128 v[58:61], v18
	ds_read_b128 v[50:53], v18 offset:16
	v_or_b32_e32 v109, 32, v91
	v_or_b32_e32 v98, 48, v91
	v_or_b32_e32 v103, 64, v91
	v_or_b32_e32 v106, 0x50, v91
	v_or_b32_e32 v110, 0x60, v91
	v_or_b32_e32 v107, 0x70, v91
	v_or_b32_e32 v108, 0x80, v91
	v_or_b32_e32 v105, 0x90, v91
	v_or_b32_e32 v104, 0xa0, v91
	v_or_b32_e32 v102, 0xb0, v91
	v_or_b32_e32 v99, 0xc0, v91
	v_or_b32_e32 v93, 0xd0, v91
	v_or_b32_e32 v90, 0xe0, v91
	v_lshl_or_b32 v89, v64, 4, v236
	v_or_b32_e32 v64, v89, v83
	v_ashrrev_i32_e32 v65, 31, v64
	v_lshlrev_b64 v[64:65], 8, v[64:65]
	v_lshl_add_u64 v[84:85], v[62:63], 0, v[64:65]
	s_lshl_b32 s2, s17, 3
	v_cmp_lt_i32_e32 vcc, v234, v229
	s_waitcnt lgkmcnt(0)
	s_waitcnt vmcnt(15)
	v_mfma_f32_16x16x4_f32 v[6:9], v144, v58, 0
	s_waitcnt vmcnt(14)
	v_mfma_f32_16x16x4_f32 v[14:17], v148, v58, 0
	v_mfma_f32_16x16x4_f32 v[6:9], v145, v59, v[6:9]
	v_mfma_f32_16x16x4_f32 v[14:17], v149, v59, v[14:17]
	v_mfma_f32_16x16x4_f32 v[6:9], v146, v60, v[6:9]
	v_mfma_f32_16x16x4_f32 v[14:17], v150, v60, v[14:17]
	v_mfma_f32_16x16x4_f32 v[2:5], v147, v61, v[6:9]
	s_mov_b64 s[100:101], 0x4000
	v_lshl_add_u64 v[238:239], v[142:143], 0, s[100:101]
	global_load_dwordx4 v[144:147], v[238:239], off
	v_mfma_f32_16x16x4_f32 v[6:9], v151, v61, v[14:17]
	s_mov_b64 s[100:101], 0x4000
	v_lshl_add_u64 v[238:239], v[142:143], 0, s[100:101]
	global_load_dwordx4 v[148:151], v[238:239], off offset:16
	s_nop 7
	s_waitcnt vmcnt(15)
	v_mfma_f32_16x16x4_f32 v[6:9], v152, v50, v[6:9]
	v_mfma_f32_16x16x4_f32 v[6:9], v153, v51, v[6:9]
	v_mfma_f32_16x16x4_f32 v[6:9], v154, v52, v[6:9]
	v_mfma_f32_16x16x4_f32 v[6:9], v155, v53, v[6:9]
	s_mov_b64 s[100:101], 0x4000
	v_lshl_add_u64 v[238:239], v[142:143], 0, s[100:101]
	global_load_dwordx4 v[152:155], v[238:239], off offset:32
	s_waitcnt vmcnt(15)
	v_mfma_f32_16x16x4_f32 v[2:5], v156, v50, v[2:5]
	v_mfma_f32_16x16x4_f32 v[2:5], v157, v51, v[2:5]
	v_mfma_f32_16x16x4_f32 v[2:5], v158, v52, v[2:5]
	v_mfma_f32_16x16x4_f32 v[10:13], v159, v53, v[2:5]
	s_mov_b64 s[100:101], 0x4000
	v_lshl_add_u64 v[238:239], v[142:143], 0, s[100:101]
	global_load_dwordx4 v[156:159], v[238:239], off offset:48
	ds_read_b128 v[54:57], v18 offset:32
	s_nop 7
	ds_read_b128 v[2:5], v18 offset:48
	s_waitcnt lgkmcnt(1)
	s_waitcnt vmcnt(15)
	v_mfma_f32_16x16x4_f32 v[10:13], v160, v54, v[10:13]
	v_mfma_f32_16x16x4_f32 v[10:13], v161, v55, v[10:13]
	v_mfma_f32_16x16x4_f32 v[10:13], v162, v56, v[10:13]
	v_mfma_f32_16x16x4_f32 v[10:13], v163, v57, v[10:13]
	s_mov_b64 s[100:101], 0x5000
	v_lshl_add_u64 v[238:239], v[142:143], 0, s[100:101]
	global_load_dwordx4 v[160:163], v[238:239], off
	s_waitcnt vmcnt(15)
	v_mfma_f32_16x16x4_f32 v[6:9], v164, v54, v[6:9]
	v_mfma_f32_16x16x4_f32 v[6:9], v165, v55, v[6:9]
	v_mfma_f32_16x16x4_f32 v[6:9], v166, v56, v[6:9]
	s_waitcnt lgkmcnt(0)
	s_waitcnt vmcnt(14)
	v_mfma_f32_16x16x4_f32 v[10:13], v168, v2, v[10:13]
	v_mfma_f32_16x16x4_f32 v[10:13], v169, v3, v[10:13]
	v_mfma_f32_16x16x4_f32 v[10:13], v170, v4, v[10:13]
	v_mfma_f32_16x16x4_f32 v[46:49], v171, v5, v[10:13]
	s_mov_b64 s[100:101], 0x5000
	v_lshl_add_u64 v[238:239], v[142:143], 0, s[100:101]
	global_load_dwordx4 v[168:171], v[238:239], off offset:32
	s_nop 8
	v_mfma_f32_16x16x4_f32 v[6:9], v167, v57, v[6:9]
	s_mov_b64 s[100:101], 0x5000
	v_lshl_add_u64 v[238:239], v[142:143], 0, s[100:101]
	global_load_dwordx4 v[164:167], v[238:239], off offset:16
	s_waitcnt vmcnt(15)
	v_mfma_f32_16x16x4_f32 v[6:9], v172, v2, v[6:9]
	v_mfma_f32_16x16x4_f32 v[6:9], v173, v3, v[6:9]
	v_mfma_f32_16x16x4_f32 v[6:9], v174, v4, v[6:9]
	v_mfma_f32_16x16x4_f32 v[34:37], v175, v5, v[6:9]
	s_mov_b64 s[100:101], 0x5000
	v_lshl_add_u64 v[238:239], v[142:143], 0, s[100:101]
	global_load_dwordx4 v[172:175], v[238:239], off offset:48
	s_nop 8
	v_or_b32_e32 v6, v109, v83
	v_ashrrev_i32_e32 v7, 31, v6
	v_lshlrev_b64 v[6:7], 8, v[6:7]
	v_lshl_add_u64 v[14:15], v[62:63], 0, v[6:7]
	s_waitcnt vmcnt(15)
	v_mfma_f32_16x16x4_f32 v[10:13], v176, v58, 0
	v_mfma_f32_16x16x4_f32 v[10:13], v177, v59, v[10:13]
	v_mfma_f32_16x16x4_f32 v[10:13], v178, v60, v[10:13]
	v_mfma_f32_16x16x4_f32 v[6:9], v179, v61, v[10:13]
	s_mov_b64 s[100:101], 0x6000
	v_lshl_add_u64 v[238:239], v[142:143], 0, s[100:101]
	global_load_dwordx4 v[176:179], v[238:239], off
	s_nop 8
	s_waitcnt vmcnt(15)
	v_mfma_f32_16x16x4_f32 v[6:9], v180, v50, v[6:9]
	v_mfma_f32_16x16x4_f32 v[6:9], v181, v51, v[6:9]
	v_mfma_f32_16x16x4_f32 v[6:9], v182, v52, v[6:9]
	v_mfma_f32_16x16x4_f32 v[6:9], v183, v53, v[6:9]
	s_mov_b64 s[100:101], 0x6000
	v_lshl_add_u64 v[238:239], v[142:143], 0, s[100:101]
	global_load_dwordx4 v[180:183], v[238:239], off offset:16
	s_waitcnt vmcnt(15)
	v_mfma_f32_16x16x4_f32 v[6:9], v184, v54, v[6:9]
	v_mfma_f32_16x16x4_f32 v[6:9], v185, v55, v[6:9]
	v_mfma_f32_16x16x4_f32 v[6:9], v186, v56, v[6:9]
	v_mfma_f32_16x16x4_f32 v[6:9], v187, v57, v[6:9]
	s_mov_b64 s[100:101], 0x6000
	v_lshl_add_u64 v[238:239], v[142:143], 0, s[100:101]
	global_load_dwordx4 v[184:187], v[238:239], off offset:32
	s_waitcnt vmcnt(15)
	v_mfma_f32_16x16x4_f32 v[6:9], v188, v2, v[6:9]
	v_mfma_f32_16x16x4_f32 v[6:9], v189, v3, v[6:9]
	v_mfma_f32_16x16x4_f32 v[6:9], v190, v4, v[6:9]
	v_mfma_f32_16x16x4_f32 v[26:29], v191, v5, v[6:9]
	s_mov_b64 s[100:101], 0x6000
	v_lshl_add_u64 v[238:239], v[142:143], 0, s[100:101]
	global_load_dwordx4 v[188:191], v[238:239], off offset:48
	s_nop 8
	v_or_b32_e32 v6, v98, v83
	v_ashrrev_i32_e32 v7, 31, v6
	v_lshlrev_b64 v[6:7], 8, v[6:7]
	v_lshl_add_u64 v[14:15], v[62:63], 0, v[6:7]
	s_waitcnt vmcnt(15)
	v_mfma_f32_16x16x4_f32 v[10:13], v192, v58, 0
	v_mfma_f32_16x16x4_f32 v[10:13], v193, v59, v[10:13]
	v_mfma_f32_16x16x4_f32 v[10:13], v194, v60, v[10:13]
	v_mfma_f32_16x16x4_f32 v[6:9], v195, v61, v[10:13]
	s_mov_b64 s[100:101], 0x7000
	v_lshl_add_u64 v[238:239], v[142:143], 0, s[100:101]
	global_load_dwordx4 v[192:195], v[238:239], off
	s_nop 8
	s_waitcnt vmcnt(15)
	v_mfma_f32_16x16x4_f32 v[6:9], v204, v50, v[6:9]
	v_mfma_f32_16x16x4_f32 v[6:9], v205, v51, v[6:9]
	v_mfma_f32_16x16x4_f32 v[6:9], v206, v52, v[6:9]
	v_mfma_f32_16x16x4_f32 v[6:9], v207, v53, v[6:9]
	s_mov_b64 s[100:101], 0x7000
	v_lshl_add_u64 v[238:239], v[142:143], 0, s[100:101]
	global_load_dwordx4 v[204:207], v[238:239], off offset:16
	s_waitcnt vmcnt(15)
	v_mfma_f32_16x16x4_f32 v[6:9], v208, v54, v[6:9]
	v_mfma_f32_16x16x4_f32 v[6:9], v209, v55, v[6:9]
	v_mfma_f32_16x16x4_f32 v[6:9], v210, v56, v[6:9]
	v_mfma_f32_16x16x4_f32 v[6:9], v211, v57, v[6:9]
	s_mov_b64 s[100:101], 0x7000
	v_lshl_add_u64 v[238:239], v[142:143], 0, s[100:101]
	global_load_dwordx4 v[208:211], v[238:239], off offset:32
	s_waitcnt vmcnt(15)
	v_mfma_f32_16x16x4_f32 v[6:9], v212, v2, v[6:9]
	v_mfma_f32_16x16x4_f32 v[6:9], v213, v3, v[6:9]
	v_mfma_f32_16x16x4_f32 v[6:9], v214, v4, v[6:9]
	v_mfma_f32_16x16x4_f32 v[18:21], v215, v5, v[6:9]
	s_mov_b64 s[100:101], 0x7000
	v_lshl_add_u64 v[238:239], v[142:143], 0, s[100:101]
	global_load_dwordx4 v[212:215], v[238:239], off offset:48
	s_nop 8
	v_or_b32_e32 v6, v103, v83
	v_ashrrev_i32_e32 v7, 31, v6
	v_lshlrev_b64 v[6:7], 8, v[6:7]
	v_lshl_add_u64 v[14:15], v[62:63], 0, v[6:7]
	s_waitcnt vmcnt(15)
	v_mfma_f32_16x16x4_f32 v[10:13], v144, v58, 0
	v_mfma_f32_16x16x4_f32 v[10:13], v145, v59, v[10:13]
	v_mfma_f32_16x16x4_f32 v[10:13], v146, v60, v[10:13]
	v_mfma_f32_16x16x4_f32 v[6:9], v147, v61, v[10:13]
	s_mov_b64 s[100:101], 0x8000
	v_lshl_add_u64 v[238:239], v[142:143], 0, s[100:101]
	global_load_dwordx4 v[144:147], v[238:239], off
	s_nop 8
	s_waitcnt vmcnt(15)
	v_mfma_f32_16x16x4_f32 v[6:9], v148, v50, v[6:9]
	v_mfma_f32_16x16x4_f32 v[6:9], v149, v51, v[6:9]
	v_mfma_f32_16x16x4_f32 v[6:9], v150, v52, v[6:9]
	v_mfma_f32_16x16x4_f32 v[6:9], v151, v53, v[6:9]
	s_mov_b64 s[100:101], 0x8000
	v_lshl_add_u64 v[238:239], v[142:143], 0, s[100:101]
	global_load_dwordx4 v[148:151], v[238:239], off offset:16
	s_waitcnt vmcnt(15)
	v_mfma_f32_16x16x4_f32 v[6:9], v152, v54, v[6:9]
	v_mfma_f32_16x16x4_f32 v[6:9], v153, v55, v[6:9]
	v_mfma_f32_16x16x4_f32 v[6:9], v154, v56, v[6:9]
	v_mfma_f32_16x16x4_f32 v[6:9], v155, v57, v[6:9]
	s_mov_b64 s[100:101], 0x8000
	v_lshl_add_u64 v[238:239], v[142:143], 0, s[100:101]
	global_load_dwordx4 v[152:155], v[238:239], off offset:32
	s_waitcnt vmcnt(15)
	v_mfma_f32_16x16x4_f32 v[6:9], v156, v2, v[6:9]
	v_mfma_f32_16x16x4_f32 v[6:9], v157, v3, v[6:9]
	v_mfma_f32_16x16x4_f32 v[6:9], v158, v4, v[6:9]
	v_mfma_f32_16x16x4_f32 v[14:17], v159, v5, v[6:9]
	s_mov_b64 s[100:101], 0x8000
	v_lshl_add_u64 v[238:239], v[142:143], 0, s[100:101]
	global_load_dwordx4 v[156:159], v[238:239], off offset:48
	s_nop 8
	v_or_b32_e32 v6, v106, v83
	v_ashrrev_i32_e32 v7, 31, v6
	v_lshlrev_b64 v[6:7], 8, v[6:7]
	v_lshl_add_u64 v[22:23], v[62:63], 0, v[6:7]
	s_waitcnt vmcnt(15)
	v_mfma_f32_16x16x4_f32 v[10:13], v160, v58, 0
	v_mfma_f32_16x16x4_f32 v[10:13], v161, v59, v[10:13]
	v_mfma_f32_16x16x4_f32 v[10:13], v162, v60, v[10:13]
	v_mfma_f32_16x16x4_f32 v[6:9], v163, v61, v[10:13]
	s_mov_b64 s[100:101], 0x9000
	v_lshl_add_u64 v[238:239], v[142:143], 0, s[100:101]
	global_load_dwordx4 v[160:163], v[238:239], off
	s_nop 8
	s_waitcnt vmcnt(14)
	v_mfma_f32_16x16x4_f32 v[6:9], v164, v50, v[6:9]
	v_mfma_f32_16x16x4_f32 v[6:9], v165, v51, v[6:9]
	v_mfma_f32_16x16x4_f32 v[6:9], v166, v52, v[6:9]
	v_mfma_f32_16x16x4_f32 v[6:9], v167, v53, v[6:9]
	s_mov_b64 s[100:101], 0x9000
	v_lshl_add_u64 v[238:239], v[142:143], 0, s[100:101]
	global_load_dwordx4 v[164:167], v[238:239], off offset:16
	s_waitcnt vmcnt(16)
	v_mfma_f32_16x16x4_f32 v[6:9], v168, v54, v[6:9]
	v_mfma_f32_16x16x4_f32 v[6:9], v169, v55, v[6:9]
	v_mfma_f32_16x16x4_f32 v[6:9], v170, v56, v[6:9]
	v_mfma_f32_16x16x4_f32 v[6:9], v171, v57, v[6:9]
	s_mov_b64 s[100:101], 0x9000
	v_lshl_add_u64 v[238:239], v[142:143], 0, s[100:101]
	global_load_dwordx4 v[168:171], v[238:239], off offset:32
	s_waitcnt vmcnt(15)
	v_mfma_f32_16x16x4_f32 v[6:9], v172, v2, v[6:9]
	v_mfma_f32_16x16x4_f32 v[6:9], v173, v3, v[6:9]
	v_mfma_f32_16x16x4_f32 v[6:9], v174, v4, v[6:9]
	v_mfma_f32_16x16x4_f32 v[22:25], v175, v5, v[6:9]
	s_mov_b64 s[100:101], 0x9000
	v_lshl_add_u64 v[238:239], v[142:143], 0, s[100:101]
	global_load_dwordx4 v[172:175], v[238:239], off offset:48
	s_nop 8
	v_or_b32_e32 v6, v110, v83
	v_ashrrev_i32_e32 v7, 31, v6
	v_lshlrev_b64 v[6:7], 8, v[6:7]
	v_lshl_add_u64 v[30:31], v[62:63], 0, v[6:7]
	s_waitcnt vmcnt(15)
	v_mfma_f32_16x16x4_f32 v[10:13], v176, v58, 0
	v_mfma_f32_16x16x4_f32 v[10:13], v177, v59, v[10:13]
	v_mfma_f32_16x16x4_f32 v[10:13], v178, v60, v[10:13]
	v_mfma_f32_16x16x4_f32 v[6:9], v179, v61, v[10:13]
	s_mov_b64 s[100:101], 0xa000
	v_lshl_add_u64 v[238:239], v[142:143], 0, s[100:101]
	global_load_dwordx4 v[176:179], v[238:239], off
	s_nop 8
	s_waitcnt vmcnt(15)
	v_mfma_f32_16x16x4_f32 v[6:9], v180, v50, v[6:9]
	v_mfma_f32_16x16x4_f32 v[6:9], v181, v51, v[6:9]
	v_mfma_f32_16x16x4_f32 v[6:9], v182, v52, v[6:9]
	v_mfma_f32_16x16x4_f32 v[6:9], v183, v53, v[6:9]
	s_mov_b64 s[100:101], 0xa000
	v_lshl_add_u64 v[238:239], v[142:143], 0, s[100:101]
	global_load_dwordx4 v[180:183], v[238:239], off offset:16
	s_waitcnt vmcnt(15)
	v_mfma_f32_16x16x4_f32 v[6:9], v184, v54, v[6:9]
	v_mfma_f32_16x16x4_f32 v[6:9], v185, v55, v[6:9]
	v_mfma_f32_16x16x4_f32 v[6:9], v186, v56, v[6:9]
	v_mfma_f32_16x16x4_f32 v[6:9], v187, v57, v[6:9]
	s_mov_b64 s[100:101], 0xa000
	v_lshl_add_u64 v[238:239], v[142:143], 0, s[100:101]
	global_load_dwordx4 v[184:187], v[238:239], off offset:32
	s_waitcnt vmcnt(15)
	v_mfma_f32_16x16x4_f32 v[6:9], v188, v2, v[6:9]
	v_mfma_f32_16x16x4_f32 v[6:9], v189, v3, v[6:9]
	v_mfma_f32_16x16x4_f32 v[6:9], v190, v4, v[6:9]
	v_mfma_f32_16x16x4_f32 v[38:41], v191, v5, v[6:9]
	s_mov_b64 s[100:101], 0xa000
	v_lshl_add_u64 v[238:239], v[142:143], 0, s[100:101]
	global_load_dwordx4 v[188:191], v[238:239], off offset:48
	s_nop 8
	v_or_b32_e32 v6, v107, v83
	v_ashrrev_i32_e32 v7, 31, v6
	v_lshlrev_b64 v[6:7], 8, v[6:7]
	v_lshl_add_u64 v[30:31], v[62:63], 0, v[6:7]
	s_waitcnt vmcnt(15)
	v_mfma_f32_16x16x4_f32 v[10:13], v192, v58, 0
	v_mfma_f32_16x16x4_f32 v[10:13], v193, v59, v[10:13]
	v_mfma_f32_16x16x4_f32 v[10:13], v194, v60, v[10:13]
	v_mfma_f32_16x16x4_f32 v[6:9], v195, v61, v[10:13]
	s_mov_b64 s[100:101], 0xb000
	v_lshl_add_u64 v[238:239], v[142:143], 0, s[100:101]
	global_load_dwordx4 v[192:195], v[238:239], off
	s_nop 8
	s_waitcnt vmcnt(15)
	v_mfma_f32_16x16x4_f32 v[6:9], v204, v50, v[6:9]
	v_mfma_f32_16x16x4_f32 v[6:9], v205, v51, v[6:9]
	v_mfma_f32_16x16x4_f32 v[6:9], v206, v52, v[6:9]
	v_mfma_f32_16x16x4_f32 v[6:9], v207, v53, v[6:9]
	s_mov_b64 s[100:101], 0xb000
	v_lshl_add_u64 v[238:239], v[142:143], 0, s[100:101]
	global_load_dwordx4 v[204:207], v[238:239], off offset:16
	s_waitcnt vmcnt(15)
	v_mfma_f32_16x16x4_f32 v[6:9], v208, v54, v[6:9]
	v_mfma_f32_16x16x4_f32 v[6:9], v209, v55, v[6:9]
	v_mfma_f32_16x16x4_f32 v[6:9], v210, v56, v[6:9]
	v_mfma_f32_16x16x4_f32 v[6:9], v211, v57, v[6:9]
	s_mov_b64 s[100:101], 0xb000
	v_lshl_add_u64 v[238:239], v[142:143], 0, s[100:101]
	global_load_dwordx4 v[208:211], v[238:239], off offset:32
	s_waitcnt vmcnt(15)
	v_mfma_f32_16x16x4_f32 v[6:9], v212, v2, v[6:9]
	v_mfma_f32_16x16x4_f32 v[6:9], v213, v3, v[6:9]
	v_mfma_f32_16x16x4_f32 v[6:9], v214, v4, v[6:9]
	v_mfma_f32_16x16x4_f32 v[42:45], v215, v5, v[6:9]
	s_mov_b64 s[100:101], 0xc000
	v_lshl_add_u64 v[238:239], v[142:143], 0, s[100:101]
	global_load_dwordx4 v[212:215], v[238:239], off
	s_nop 8
	v_or_b32_e32 v6, v108, v83
	v_ashrrev_i32_e32 v7, 31, v6
	v_lshlrev_b64 v[6:7], 8, v[6:7]
	v_lshl_add_u64 v[30:31], v[62:63], 0, v[6:7]
	s_waitcnt vmcnt(15)
	v_mfma_f32_16x16x4_f32 v[10:13], v144, v58, 0
	v_mfma_f32_16x16x4_f32 v[10:13], v145, v59, v[10:13]
	v_mfma_f32_16x16x4_f32 v[10:13], v146, v60, v[10:13]
	v_mfma_f32_16x16x4_f32 v[6:9], v147, v61, v[10:13]
	s_mov_b64 s[100:101], 0xd000
	v_lshl_add_u64 v[238:239], v[142:143], 0, s[100:101]
	global_load_dwordx4 v[144:147], v[238:239], off
	s_nop 8
	s_waitcnt vmcnt(15)
	v_mfma_f32_16x16x4_f32 v[6:9], v148, v50, v[6:9]
	v_mfma_f32_16x16x4_f32 v[6:9], v149, v51, v[6:9]
	v_mfma_f32_16x16x4_f32 v[6:9], v150, v52, v[6:9]
	v_mfma_f32_16x16x4_f32 v[6:9], v151, v53, v[6:9]
	s_mov_b64 s[100:101], 0xe000
	v_lshl_add_u64 v[238:239], v[142:143], 0, s[100:101]
	global_load_dwordx4 v[148:151], v[238:239], off
	s_waitcnt vmcnt(15)
	v_mfma_f32_16x16x4_f32 v[6:9], v152, v54, v[6:9]
	v_mfma_f32_16x16x4_f32 v[6:9], v153, v55, v[6:9]
	v_mfma_f32_16x16x4_f32 v[6:9], v154, v56, v[6:9]
	v_mfma_f32_16x16x4_f32 v[6:9], v155, v57, v[6:9]
	s_mov_b64 s[100:101], 0xf000
	v_lshl_add_u64 v[238:239], v[142:143], 0, s[100:101]
	global_load_dwordx4 v[152:155], v[238:239], off
	s_waitcnt vmcnt(15)
	v_mfma_f32_16x16x4_f32 v[6:9], v156, v2, v[6:9]
	v_mfma_f32_16x16x4_f32 v[6:9], v157, v3, v[6:9]
	v_mfma_f32_16x16x4_f32 v[6:9], v158, v4, v[6:9]
	v_mfma_f32_16x16x4_f32 v[30:33], v159, v5, v[6:9]
	s_mov_b64 s[100:101], 0xc000
	v_lshl_add_u64 v[238:239], v[142:143], 0, s[100:101]
	global_load_dwordx4 v[156:159], v[238:239], off offset:16
	s_nop 8
	v_or_b32_e32 v6, v105, v83
	v_ashrrev_i32_e32 v7, 31, v6
	v_lshlrev_b64 v[6:7], 8, v[6:7]
	v_lshl_add_u64 v[66:67], v[62:63], 0, v[6:7]
	s_waitcnt vmcnt(15)
	v_mfma_f32_16x16x4_f32 v[10:13], v160, v58, 0
	v_mfma_f32_16x16x4_f32 v[10:13], v161, v59, v[10:13]
	v_mfma_f32_16x16x4_f32 v[10:13], v162, v60, v[10:13]
	v_mfma_f32_16x16x4_f32 v[6:9], v163, v61, v[10:13]
	s_mov_b64 s[100:101], 0xc000
	v_lshl_add_u64 v[238:239], v[142:143], 0, s[100:101]
	global_load_dwordx4 v[160:163], v[238:239], off offset:32
	s_nop 8
	s_waitcnt vmcnt(15)
	v_mfma_f32_16x16x4_f32 v[6:9], v164, v50, v[6:9]
	v_mfma_f32_16x16x4_f32 v[6:9], v165, v51, v[6:9]
	v_mfma_f32_16x16x4_f32 v[6:9], v166, v52, v[6:9]
	v_mfma_f32_16x16x4_f32 v[6:9], v167, v53, v[6:9]
	s_mov_b64 s[100:101], 0xd000
	v_lshl_add_u64 v[238:239], v[142:143], 0, s[100:101]
	global_load_dwordx4 v[164:167], v[238:239], off offset:16
	s_waitcnt vmcnt(15)
	v_mfma_f32_16x16x4_f32 v[6:9], v168, v54, v[6:9]
	v_mfma_f32_16x16x4_f32 v[6:9], v169, v55, v[6:9]
	v_mfma_f32_16x16x4_f32 v[6:9], v170, v56, v[6:9]
	v_mfma_f32_16x16x4_f32 v[6:9], v171, v57, v[6:9]
	s_mov_b64 s[100:101], 0xd000
	v_lshl_add_u64 v[238:239], v[142:143], 0, s[100:101]
	global_load_dwordx4 v[168:171], v[238:239], off offset:32
	s_waitcnt vmcnt(15)
	v_mfma_f32_16x16x4_f32 v[6:9], v172, v2, v[6:9]
	v_mfma_f32_16x16x4_f32 v[6:9], v173, v3, v[6:9]
	v_mfma_f32_16x16x4_f32 v[6:9], v174, v4, v[6:9]
	v_mfma_f32_16x16x4_f32 v[10:13], v175, v5, v[6:9]
	s_mov_b64 s[100:101], 0xe000
	v_lshl_add_u64 v[238:239], v[142:143], 0, s[100:101]
	global_load_dwordx4 v[172:175], v[238:239], off offset:16
	s_nop 8
	v_or_b32_e32 v6, v104, v83
	v_ashrrev_i32_e32 v7, 31, v6
	v_lshlrev_b64 v[6:7], 8, v[6:7]
	v_lshl_add_u64 v[70:71], v[62:63], 0, v[6:7]
	s_waitcnt vmcnt(15)
	v_mfma_f32_16x16x4_f32 v[66:69], v176, v58, 0
	v_mfma_f32_16x16x4_f32 v[66:69], v177, v59, v[66:69]
	v_mfma_f32_16x16x4_f32 v[66:69], v178, v60, v[66:69]
	v_mfma_f32_16x16x4_f32 v[6:9], v179, v61, v[66:69]
	s_mov_b64 s[100:101], 0xe000
	v_lshl_add_u64 v[238:239], v[142:143], 0, s[100:101]
	global_load_dwordx4 v[176:179], v[238:239], off offset:32
	s_nop 8
	s_waitcnt vmcnt(15)
	v_mfma_f32_16x16x4_f32 v[6:9], v180, v50, v[6:9]
	v_mfma_f32_16x16x4_f32 v[6:9], v181, v51, v[6:9]
	v_mfma_f32_16x16x4_f32 v[6:9], v182, v52, v[6:9]
	v_mfma_f32_16x16x4_f32 v[6:9], v183, v53, v[6:9]
	s_mov_b64 s[100:101], 0xf000
	v_lshl_add_u64 v[238:239], v[142:143], 0, s[100:101]
	global_load_dwordx4 v[180:183], v[238:239], off offset:16
	s_waitcnt vmcnt(15)
	v_mfma_f32_16x16x4_f32 v[6:9], v184, v54, v[6:9]
	v_mfma_f32_16x16x4_f32 v[6:9], v185, v55, v[6:9]
	v_mfma_f32_16x16x4_f32 v[6:9], v186, v56, v[6:9]
	v_mfma_f32_16x16x4_f32 v[6:9], v187, v57, v[6:9]
	s_mov_b64 s[100:101], 0xf000
	v_lshl_add_u64 v[238:239], v[142:143], 0, s[100:101]
	global_load_dwordx4 v[184:187], v[238:239], off offset:32
	s_waitcnt vmcnt(15)
	v_mfma_f32_16x16x4_f32 v[6:9], v188, v2, v[6:9]
	v_or_b32_e32 v66, v102, v83
	v_mfma_f32_16x16x4_f32 v[6:9], v189, v3, v[6:9]
	v_ashrrev_i32_e32 v67, 31, v66
	v_lshlrev_b64 v[66:67], 8, v[66:67]
	v_lshl_add_u64 v[100:101], v[62:63], 0, v[66:67]
	v_mfma_f32_16x16x4_f32 v[6:9], v190, v4, v[6:9]
	v_mfma_f32_16x16x4_f32 v[6:9], v191, v5, v[6:9]
	s_mov_b64 s[100:101], 0xb000
	v_lshl_add_u64 v[238:239], v[142:143], 0, s[100:101]
	global_load_dwordx4 v[188:191], v[238:239], off offset:48
	s_waitcnt vmcnt(15)
	v_mfma_f32_16x16x4_f32 v[70:73], v192, v58, 0
	v_mfma_f32_16x16x4_f32 v[70:73], v193, v59, v[70:73]
	v_mfma_f32_16x16x4_f32 v[70:73], v194, v60, v[70:73]
	v_mfma_f32_16x16x4_f32 v[66:69], v195, v61, v[70:73]
	s_mov_b64 s[100:101], 0xc000
	v_lshl_add_u64 v[238:239], v[142:143], 0, s[100:101]
	global_load_dwordx4 v[192:195], v[238:239], off offset:48
	s_nop 8
	s_waitcnt vmcnt(15)
	v_mfma_f32_16x16x4_f32 v[66:69], v204, v50, v[66:69]
	v_mfma_f32_16x16x4_f32 v[66:69], v205, v51, v[66:69]
	v_mfma_f32_16x16x4_f32 v[66:69], v206, v52, v[66:69]
	v_mfma_f32_16x16x4_f32 v[66:69], v207, v53, v[66:69]
	s_mov_b64 s[100:101], 0xd000
	v_lshl_add_u64 v[238:239], v[142:143], 0, s[100:101]
	global_load_dwordx4 v[204:207], v[238:239], off offset:48
	s_waitcnt vmcnt(15)
	v_mfma_f32_16x16x4_f32 v[66:69], v208, v54, v[66:69]
	v_or_b32_e32 v70, v99, v83
	v_mfma_f32_16x16x4_f32 v[66:69], v209, v55, v[66:69]
	v_ashrrev_i32_e32 v71, 31, v70
	v_lshlrev_b64 v[70:71], 8, v[70:71]
	v_lshl_add_u64 v[74:75], v[62:63], 0, v[70:71]
	v_mfma_f32_16x16x4_f32 v[66:69], v210, v56, v[66:69]
	v_mfma_f32_16x16x4_f32 v[94:97], v211, v57, v[66:69]
	s_mov_b64 s[100:101], 0xe000
	v_lshl_add_u64 v[238:239], v[142:143], 0, s[100:101]
	global_load_dwordx4 v[208:211], v[238:239], off offset:48
	s_nop 8
	s_waitcnt vmcnt(15)
	v_mfma_f32_16x16x4_f32 v[70:73], v212, v58, 0
	v_or_b32_e32 v66, v93, v83
	v_mfma_f32_16x16x4_f32 v[70:73], v213, v59, v[70:73]
	v_ashrrev_i32_e32 v67, 31, v66
	v_lshlrev_b64 v[66:67], 8, v[66:67]
	v_lshl_add_u64 v[76:77], v[62:63], 0, v[66:67]
	v_mfma_f32_16x16x4_f32 v[70:73], v214, v60, v[70:73]
	v_mfma_f32_16x16x4_f32 v[112:115], v215, v61, v[70:73]
	s_mov_b64 s[100:101], 0xf000
	v_lshl_add_u64 v[238:239], v[142:143], 0, s[100:101]
	global_load_dwordx4 v[212:215], v[238:239], off offset:48
	s_waitcnt vmcnt(15)
	v_mfma_f32_16x16x4_f32 v[70:73], v144, v58, 0
	v_or_b32_e32 v66, v90, v83
	v_mfma_f32_16x16x4_f32 v[70:73], v145, v59, v[70:73]
	v_ashrrev_i32_e32 v67, 31, v66
	v_lshlrev_b64 v[66:67], 8, v[66:67]
	v_lshl_add_u64 v[86:87], v[62:63], 0, v[66:67]
	v_mfma_f32_16x16x4_f32 v[70:73], v146, v60, v[70:73]
	v_mfma_f32_16x16x4_f32 v[70:73], v147, v61, v[70:73]
	s_waitcnt vmcnt(14)
	v_mfma_f32_16x16x4_f32 v[78:81], v148, v58, 0
	v_mfma_f32_16x16x4_f32 v[78:81], v149, v59, v[78:81]
	v_mfma_f32_16x16x4_f32 v[78:81], v150, v60, v[78:81]
	v_mfma_f32_16x16x4_f32 v[66:69], v151, v61, v[78:81]
	s_waitcnt vmcnt(13)
	v_mfma_f32_16x16x4_f32 v[78:81], v152, v58, 0
	v_mfma_f32_16x16x4_f32 v[78:81], v153, v59, v[78:81]
	v_mfma_f32_16x16x4_f32 v[78:81], v154, v60, v[78:81]
	v_mfma_f32_16x16x4_f32 v[62:65], v155, v61, v[78:81]
	s_nop 8
	s_waitcnt vmcnt(12)
	v_mfma_f32_16x16x4_f32 v[112:115], v156, v50, v[112:115]
	v_mfma_f32_16x16x4_f32 v[112:115], v157, v51, v[112:115]
	v_mfma_f32_16x16x4_f32 v[112:115], v158, v52, v[112:115]
	v_mfma_f32_16x16x4_f32 v[58:61], v159, v53, v[112:115]
	s_nop 8
	s_waitcnt vmcnt(11)
	v_mfma_f32_16x16x4_f32 v[58:61], v160, v54, v[58:61]
	v_mfma_f32_16x16x4_f32 v[58:61], v161, v55, v[58:61]
	v_mfma_f32_16x16x4_f32 v[58:61], v162, v56, v[58:61]
	v_mfma_f32_16x16x4_f32 v[112:115], v163, v57, v[58:61]
	s_nop 8
	s_waitcnt vmcnt(10)
	v_mfma_f32_16x16x4_f32 v[70:73], v164, v50, v[70:73]
	v_mfma_f32_16x16x4_f32 v[70:73], v165, v51, v[70:73]
	v_mfma_f32_16x16x4_f32 v[70:73], v166, v52, v[70:73]
	v_mfma_f32_16x16x4_f32 v[58:61], v167, v53, v[70:73]
	s_nop 8
	s_nop 0
	s_waitcnt vmcnt(9)
	v_mfma_f32_16x16x4_f32 v[58:61], v168, v54, v[58:61]
	v_mfma_f32_16x16x4_f32 v[58:61], v169, v55, v[58:61]
	v_mfma_f32_16x16x4_f32 v[58:61], v170, v56, v[58:61]
	v_mfma_f32_16x16x4_f32 v[70:73], v171, v57, v[58:61]
	s_nop 8
	s_waitcnt vmcnt(8)
	v_mfma_f32_16x16x4_f32 v[66:69], v172, v50, v[66:69]
	v_mfma_f32_16x16x4_f32 v[66:69], v173, v51, v[66:69]
	v_mfma_f32_16x16x4_f32 v[66:69], v174, v52, v[66:69]
	v_mfma_f32_16x16x4_f32 v[58:61], v175, v53, v[66:69]
	s_nop 8
	s_waitcnt vmcnt(7)
	v_mfma_f32_16x16x4_f32 v[58:61], v176, v54, v[58:61]
	v_mfma_f32_16x16x4_f32 v[58:61], v177, v55, v[58:61]
	v_mfma_f32_16x16x4_f32 v[58:61], v178, v56, v[58:61]
	v_mfma_f32_16x16x4_f32 v[58:61], v179, v57, v[58:61]
	s_waitcnt vmcnt(6)
	v_mfma_f32_16x16x4_f32 v[62:65], v180, v50, v[62:65]
	v_mfma_f32_16x16x4_f32 v[62:65], v181, v51, v[62:65]
	v_mfma_f32_16x16x4_f32 v[62:65], v182, v52, v[62:65]
	v_mfma_f32_16x16x4_f32 v[50:53], v183, v53, v[62:65]
	s_nop 8
	s_waitcnt vmcnt(5)
	v_mfma_f32_16x16x4_f32 v[50:53], v184, v54, v[50:53]
	v_mfma_f32_16x16x4_f32 v[50:53], v185, v55, v[50:53]
	v_mfma_f32_16x16x4_f32 v[50:53], v186, v56, v[50:53]
	s_waitcnt vmcnt(4)
	v_mfma_f32_16x16x4_f32 v[94:97], v188, v2, v[94:97]
	v_and_b32_e32 v78, 7, v82
	v_mfma_f32_16x16x4_f32 v[54:57], v187, v57, v[50:53]
	s_nop 6
	v_or_b32_e32 v50, s2, v78
	v_cvt_f32_u32_e32 v62, v50
	v_lshrrev_b32_e32 v50, 2, v82
	v_and_b32_e32 v101, 12, v50
	v_or_b32_e32 v91, v91, v101
	v_cvt_f32_i32_e32 v63, v91
	v_fmamk_f32 v100, v62, 0xbcc4df2d, v222
	v_mfma_f32_16x16x4_f32 v[50:53], v189, v3, v[94:97]
	v_or_b32_e32 v79, 1, v91
	v_mul_f32_e32 v62, 0xba001002, v63
	v_mul_f32_e64 v62, v62, |v100|
	v_mul_f32_e32 v62, 0x3fb8aa3b, v62
	v_exp_f32_e32 v62, v62
	v_cvt_f32_i32_e32 v63, v79
	v_or_b32_e32 v98, v98, v101
	v_mfma_f32_16x16x4_f32 v[50:53], v190, v4, v[50:53]
	v_or_b32_e32 v80, 2, v91
	v_mul_f32_e32 v86, v62, v46
	v_cvt_f32_i32_e32 v62, v80
	v_mul_f32_e32 v46, 0xba001002, v63
	v_mul_f32_e64 v46, |v100|, v46
	v_mul_f32_e32 v46, 0x3fb8aa3b, v46
	v_mul_f32_e32 v62, 0xba001002, v62
	v_mul_f32_e64 v62, |v100|, v62
	v_mfma_f32_16x16x4_f32 v[50:53], v191, v5, v[50:53]
	v_or_b32_e32 v81, 3, v91
	v_mul_f32_e32 v94, 0x3fb8aa3b, v62
	v_cvt_f32_i32_e32 v87, v81
	v_exp_f32_e32 v46, v46
	v_exp_f32_e32 v94, v94
	v_or_b32_e32 v107, v107, v101
	v_mul_f32_e32 v87, 0xba001002, v87
	s_waitcnt vmcnt(3)
	v_mfma_f32_16x16x4_f32 v[62:65], v192, v2, v[112:115]
	v_mul_f32_e64 v87, |v100|, v87
	v_mul_f32_e32 v87, 0x3fb8aa3b, v87
	v_exp_f32_e32 v97, v87
	v_or_b32_e32 v87, v92, v101
	v_cvt_f32_i32_e32 v111, v87
	v_mul_f32_e32 v96, v46, v47
	v_mul_f32_e32 v95, v94, v48
	v_mfma_f32_16x16x4_f32 v[62:65], v193, v3, v[62:65]
	v_mul_f32_e32 v46, 0xba001002, v111
	v_mul_f32_e64 v46, |v100|, v46
	v_mul_f32_e32 v46, 0x3fb8aa3b, v46
	v_mul_f32_e32 v92, v97, v49
	v_exp_f32_e32 v97, v46
	v_or_b32_e32 v94, 1, v87
	v_cvt_f32_i32_e32 v111, v94
	v_mfma_f32_16x16x4_f32 v[46:49], v194, v4, v[62:65]
	s_nop 1
	v_or_b32_e32 v84, 2, v87
	v_mul_f32_e32 v85, v97, v34
	v_cvt_f32_i32_e32 v97, v84
	v_mul_f32_e32 v34, 0xba001002, v111
	v_mul_f32_e64 v34, |v100|, v34
	v_mul_f32_e32 v34, 0x3fb8aa3b, v34
	v_mul_f32_e32 v111, 0xba001002, v97
	v_or_b32_e32 v97, 3, v87
	v_cvt_f32_i32_e32 v112, v97
	v_mul_f32_e64 v111, |v100|, v111
	v_mul_f32_e32 v111, 0x3fb8aa3b, v111
	v_exp_f32_e32 v34, v34
	v_mul_f32_e32 v112, 0xba001002, v112
	v_mul_f32_e64 v112, |v100|, v112
	v_mul_f32_e32 v116, 0x3fb8aa3b, v112
	s_waitcnt vmcnt(2)
	v_mfma_f32_16x16x4_f32 v[112:115], v204, v2, v[70:73]
	v_exp_f32_e32 v111, v111
	v_exp_f32_e32 v71, v116
	v_mul_f32_e32 v74, v34, v35
	v_or_b32_e32 v70, v109, v101
	v_mul_f32_e32 v72, v111, v36
	v_mul_f32_e32 v71, v71, v37
	v_cvt_f32_i32_e32 v73, v70
	v_mfma_f32_16x16x4_f32 v[34:37], v205, v3, v[112:115]
	v_mul_f32_e32 v73, 0xba001002, v73
	v_mul_f32_e64 v73, |v100|, v73
	v_mul_f32_e32 v73, 0x3fb8aa3b, v73
	v_exp_f32_e32 v75, v73
	v_or_b32_e32 v73, 1, v70
	v_mfma_f32_16x16x4_f32 v[34:37], v206, v4, v[34:37]
	v_cvt_f32_i32_e32 v109, v73
	v_or_b32_e32 v76, 2, v70
	v_mul_f32_e32 v75, v75, v26
	v_mul_f32_e32 v26, 0xba001002, v109
	v_cvt_f32_i32_e32 v109, v76
	v_mul_f32_e64 v26, |v100|, v26
	v_mfma_f32_16x16x4_f32 v[34:37], v207, v5, v[34:37]
	v_or_b32_e32 v77, 3, v70
	v_cvt_f32_i32_e32 v111, v77
	v_mul_f32_e32 v26, 0x3fb8aa3b, v26
	v_mul_f32_e32 v109, 0xba001002, v109
	v_exp_f32_e32 v26, v26
	v_mul_f32_e32 v111, 0xba001002, v111
	v_mul_f32_e64 v109, |v100|, v109
	s_waitcnt vmcnt(1)
	v_mfma_f32_16x16x4_f32 v[112:115], v208, v2, v[58:61]
	v_mul_f32_e64 v111, |v100|, v111
	v_cvt_f32_i32_e32 v60, v98
	v_mul_f32_e32 v109, 0x3fb8aa3b, v109
	v_mul_f32_e32 v111, 0x3fb8aa3b, v111
	v_exp_f32_e32 v109, v109
	v_exp_f32_e32 v111, v111
	v_mul_f32_e32 v61, v26, v27
	v_mul_f32_e32 v26, 0xba001002, v60
	v_mul_f32_e64 v26, |v100|, v26
	v_mul_f32_e32 v59, v109, v28
	v_mul_f32_e32 v58, v111, v29
	v_mul_f32_e32 v60, 0x3fb8aa3b, v26
	v_mfma_f32_16x16x4_f32 v[26:29], v209, v3, v[112:115]
	v_exp_f32_e32 v66, v60
	v_or_b32_e32 v60, 1, v98
	v_cvt_f32_i32_e32 v67, v60
	v_mul_f32_e32 v18, v66, v18
	v_or_b32_e32 v66, 2, v98
	v_mul_f32_e32 v67, 0xba001002, v67
	v_mfma_f32_16x16x4_f32 v[26:29], v210, v4, v[26:29]
	v_cvt_f32_i32_e32 v68, v66
	v_mul_f32_e64 v67, |v100|, v67
	v_mul_f32_e32 v67, 0x3fb8aa3b, v67
	v_exp_f32_e32 v109, v67
	v_or_b32_e32 v67, 3, v98
	v_mul_f32_e32 v68, 0xba001002, v68
	v_mul_f32_e64 v68, |v100|, v68
	v_mfma_f32_16x16x4_f32 v[26:29], v211, v5, v[26:29]
	v_cvt_f32_i32_e32 v69, v67
	v_mul_f32_e32 v68, 0x3fb8aa3b, v68
	v_exp_f32_e32 v111, v68
	v_mul_f32_e32 v68, 0xba001002, v69
	v_mul_f32_e64 v68, |v100|, v68
	v_mul_f32_e32 v68, 0x3fb8aa3b, v68
	s_waitcnt vmcnt(0)
	v_mfma_f32_16x16x4_f32 v[54:57], v212, v2, v[54:57]
	v_exp_f32_e32 v112, v68
	v_or_b32_e32 v68, v103, v101
	v_cvt_f32_i32_e32 v113, v68
	v_mul_f32_e32 v69, v111, v20
	v_mul_f32_e32 v20, v112, v21
	v_mul_f32_e32 v103, v109, v19
	v_mul_f32_e32 v21, 0xba001002, v113
	v_mul_f32_e64 v21, |v100|, v21
	v_mul_f32_e32 v21, 0x3fb8aa3b, v21
	v_mfma_f32_16x16x4_f32 v[54:57], v213, v3, v[54:57]
	v_or_b32_e32 v19, 1, v68
	v_exp_f32_e32 v62, v21
	v_or_b32_e32 v21, 2, v68
	v_cvt_f32_i32_e32 v2, v19
	v_cvt_f32_i32_e32 v109, v21
	v_mul_f32_e32 v2, 0xba001002, v2
	v_mul_f32_e32 v3, 0xba001002, v109
	v_mul_f32_e64 v2, |v100|, v2
	v_mul_f32_e64 v3, |v100|, v3
	v_mul_f32_e32 v2, 0x3fb8aa3b, v2
	v_mul_f32_e32 v3, 0x3fb8aa3b, v3
	v_mfma_f32_16x16x4_f32 v[112:115], v214, v4, v[54:57]
	v_or_b32_e32 v54, 3, v68
	v_exp_f32_e32 v2, v2
	v_exp_f32_e32 v3, v3
	v_cvt_f32_i32_e32 v4, v54
	v_mul_f32_e32 v56, v62, v14
	v_mul_f32_e32 v55, v2, v15
	v_mul_f32_e32 v15, v3, v16
	v_mul_f32_e32 v16, 0xba001002, v4
	v_or_b32_e32 v14, v106, v101
	v_cvt_f32_i32_e32 v57, v14
	v_mul_f32_e64 v16, |v100|, v16
	v_mul_f32_e32 v16, 0x3fb8aa3b, v16
	v_exp_f32_e32 v62, v16
	v_or_b32_e32 v16, 1, v14
	v_cvt_f32_i32_e32 v63, v16
	v_mul_f32_e32 v57, 0xba001002, v57
	v_mul_f32_e64 v57, |v100|, v57
	v_mul_f32_e32 v57, 0x3fb8aa3b, v57
	v_mfma_f32_16x16x4_f32 v[46:49], v195, v5, v[46:49]
	v_mul_f32_e32 v64, v62, v17
	v_mfma_f32_16x16x4_f32 v[2:5], v215, v5, v[112:115]
	v_exp_f32_e32 v65, v57
	v_mul_f32_e32 v57, 0xba001002, v63
	v_mul_f32_e64 v57, |v100|, v57
	v_mul_f32_e32 v57, 0x3fb8aa3b, v57
	v_exp_f32_e32 v63, v57
	v_or_b32_e32 v57, 2, v14
	v_cvt_f32_i32_e32 v106, v57
	v_mul_f32_e32 v62, v65, v22
	v_or_b32_e32 v22, 3, v14
	v_mul_f32_e32 v23, v63, v23
	v_mul_f32_e32 v17, 0xba001002, v106
	v_cvt_f32_i32_e32 v63, v22
	v_mul_f32_e64 v17, |v100|, v17
	v_mul_f32_e32 v17, 0x3fb8aa3b, v17
	v_exp_f32_e32 v65, v17
	v_or_b32_e32 v17, v110, v101
	v_cvt_f32_i32_e32 v106, v17
	v_mul_f32_e32 v63, 0xba001002, v63
	v_mul_f32_e64 v63, |v100|, v63
	v_mul_f32_e32 v63, 0x3fb8aa3b, v63
	v_exp_f32_e32 v109, v63
	v_mul_f32_e32 v63, 0xba001002, v106
	v_mul_f32_e64 v63, |v100|, v63
	v_mul_f32_e32 v63, 0x3fb8aa3b, v63
	v_exp_f32_e32 v110, v63
	v_or_b32_e32 v63, 1, v17
	v_cvt_f32_i32_e32 v111, v63
	v_mul_f32_e32 v106, v65, v24
	v_mul_f32_e32 v38, v110, v38
	v_or_b32_e32 v24, 2, v17
	v_mul_f32_e32 v65, 0xba001002, v111
	v_mul_f32_e64 v65, |v100|, v65
	v_mul_f32_e32 v65, 0x3fb8aa3b, v65
	v_exp_f32_e32 v110, v65
	v_or_b32_e32 v65, 3, v17
	v_mul_f32_e32 v25, v109, v25
	v_cvt_f32_i32_e32 v109, v24
	v_cvt_f32_i32_e32 v111, v65
	v_cvt_f32_i32_e32 v112, v107
	v_mul_f32_e32 v110, v110, v39
	v_mul_f32_e32 v109, 0xba001002, v109
	v_mul_f32_e32 v111, 0xba001002, v111
	v_mul_f32_e64 v109, |v100|, v109
	v_mul_f32_e64 v111, |v100|, v111
	v_mul_f32_e32 v109, 0x3fb8aa3b, v109
	v_mul_f32_e32 v111, 0x3fb8aa3b, v111
	v_exp_f32_e32 v109, v109
	v_exp_f32_e32 v111, v111
	v_or_b32_e32 v39, 1, v107
	v_mul_f32_e32 v109, v109, v40
	v_mul_f32_e32 v40, v111, v41
	v_mul_f32_e32 v41, 0xba001002, v112
	v_cvt_f32_i32_e32 v111, v39
	v_mul_f32_e64 v41, |v100|, v41
	v_mul_f32_e32 v41, 0x3fb8aa3b, v41
	v_exp_f32_e32 v112, v41
	v_or_b32_e32 v41, 2, v107
	v_cvt_f32_i32_e32 v113, v41
	v_mul_f32_e32 v111, 0xba001002, v111
	v_mul_f32_e64 v111, |v100|, v111
	v_mul_f32_e32 v111, 0x3fb8aa3b, v111
	v_exp_f32_e32 v114, v111
	v_mul_f32_e32 v111, 0xba001002, v113
	v_mul_f32_e64 v111, |v100|, v111
	v_mul_f32_e32 v111, 0x3fb8aa3b, v111
	v_exp_f32_e32 v115, v111
	v_or_b32_e32 v111, 3, v107
	v_cvt_f32_i32_e32 v113, v111
	v_mul_f32_e32 v44, v115, v44
	v_mul_f32_e32 v113, 0xba001002, v113
	v_mul_f32_e64 v113, |v100|, v113
	v_mul_f32_e32 v113, 0x3fb8aa3b, v113
	v_exp_f32_e32 v116, v113
	v_mul_f32_e32 v113, v112, v42
	v_mul_f32_e32 v112, v114, v43
	v_or_b32_e32 v43, v108, v101
	v_mul_f32_e32 v42, v116, v45
	v_cvt_f32_i32_e32 v45, v43
	v_mul_f32_e32 v108, 0xba001002, v45
	v_or_b32_e32 v45, 1, v43
	v_cvt_f32_i32_e32 v114, v45
	v_mul_f32_e64 v108, |v100|, v108
	v_mul_f32_e32 v108, 0x3fb8aa3b, v108
	v_exp_f32_e32 v115, v108
	v_mul_f32_e32 v108, 0xba001002, v114
	v_mul_f32_e64 v108, |v100|, v108
	v_mul_f32_e32 v108, 0x3fb8aa3b, v108
	v_exp_f32_e32 v117, v108
	v_or_b32_e32 v108, 2, v43
	v_cvt_f32_i32_e32 v114, v108
	v_mul_f32_e32 v114, 0xba001002, v114
	v_mul_f32_e64 v114, |v100|, v114
	v_mul_f32_e32 v114, 0x3fb8aa3b, v114
	v_exp_f32_e32 v118, v114
	v_or_b32_e32 v114, 3, v43
	v_cvt_f32_i32_e32 v116, v114
	v_mul_f32_e32 v116, 0xba001002, v116
	v_mul_f32_e64 v116, |v100|, v116
	v_mul_f32_e32 v116, 0x3fb8aa3b, v116
	v_exp_f32_e32 v119, v116
	v_mul_f32_e32 v116, v115, v30
	v_mul_f32_e32 v115, v117, v31
	v_mul_f32_e32 v31, v118, v32
	v_or_b32_e32 v32, v105, v101
	v_mul_f32_e32 v30, v119, v33
	v_cvt_f32_i32_e32 v33, v32
	v_mul_f32_e32 v33, 0xba001002, v33
	v_mul_f32_e64 v33, |v100|, v33
	v_mul_f32_e32 v33, 0x3fb8aa3b, v33
	v_exp_f32_e32 v118, v33
	v_or_b32_e32 v33, 1, v32
	v_cvt_f32_i32_e32 v105, v33
	v_mul_f32_e32 v105, 0xba001002, v105
	v_mul_f32_e64 v105, |v100|, v105
	v_mul_f32_e32 v105, 0x3fb8aa3b, v105
	v_exp_f32_e32 v120, v105
	v_or_b32_e32 v105, 2, v32
	v_cvt_f32_i32_e32 v117, v105
	v_mul_f32_e32 v117, 0xba001002, v117
	v_mul_f32_e64 v117, |v100|, v117
	v_mul_f32_e32 v117, 0x3fb8aa3b, v117
	v_exp_f32_e32 v121, v117
	v_or_b32_e32 v117, 3, v32
	v_cvt_f32_i32_e32 v119, v117
	v_mul_f32_e32 v12, v121, v12
	v_mul_f32_e32 v119, 0xba001002, v119
	v_mul_f32_e64 v119, |v100|, v119
	v_mul_f32_e32 v119, 0x3fb8aa3b, v119
	v_exp_f32_e32 v122, v119
	v_mul_f32_e32 v119, v118, v10
	v_mul_f32_e32 v118, v120, v11
	v_or_b32_e32 v11, v104, v101
	v_mul_f32_e32 v10, v122, v13
	v_cvt_f32_i32_e32 v13, v11
	v_mul_f32_e32 v13, 0xba001002, v13
	v_mul_f32_e64 v13, |v100|, v13
	v_mul_f32_e32 v13, 0x3fb8aa3b, v13
	v_exp_f32_e32 v121, v13
	v_or_b32_e32 v13, 1, v11
	v_cvt_f32_i32_e32 v104, v13
	v_mul_f32_e32 v104, 0xba001002, v104
	v_mul_f32_e64 v104, |v100|, v104
	v_mul_f32_e32 v104, 0x3fb8aa3b, v104
	v_exp_f32_e32 v123, v104
	v_or_b32_e32 v104, 2, v11
	v_cvt_f32_i32_e32 v120, v104
	v_mul_f32_e32 v120, 0xba001002, v120
	v_mul_f32_e64 v120, |v100|, v120
	v_mul_f32_e32 v120, 0x3fb8aa3b, v120
	v_exp_f32_e32 v124, v120
	v_or_b32_e32 v120, 3, v11
	v_cvt_f32_i32_e32 v122, v120
	v_mul_f32_e32 v122, 0xba001002, v122
	v_mul_f32_e64 v122, |v100|, v122
	v_mul_f32_e32 v122, 0x3fb8aa3b, v122
	v_exp_f32_e32 v125, v122
	v_mul_f32_e32 v122, v121, v6
	v_mul_f32_e32 v121, v123, v7
	v_mul_f32_e32 v7, v124, v8
	v_or_b32_e32 v8, v102, v101
	v_mul_f32_e32 v6, v125, v9
	v_cvt_f32_i32_e32 v9, v8
	v_mul_f32_e32 v9, 0xba001002, v9
	v_mul_f32_e64 v9, |v100|, v9
	v_mul_f32_e32 v9, 0x3fb8aa3b, v9
	v_exp_f32_e32 v124, v9
	v_or_b32_e32 v9, 1, v8
	v_cvt_f32_i32_e32 v102, v9
	v_mul_f32_e32 v102, 0xba001002, v102
	v_mul_f32_e64 v102, |v100|, v102
	v_mul_f32_e32 v102, 0x3fb8aa3b, v102
	v_exp_f32_e32 v126, v102
	v_or_b32_e32 v102, 2, v8
	v_cvt_f32_i32_e32 v123, v102
	v_mul_f32_e32 v123, 0xba001002, v123
	v_mul_f32_e64 v123, |v100|, v123
	v_mul_f32_e32 v123, 0x3fb8aa3b, v123
	v_exp_f32_e32 v127, v123
	v_or_b32_e32 v123, 3, v8
	v_cvt_f32_i32_e32 v125, v123
	v_mul_f32_e32 v52, v127, v52
	v_mul_f32_e32 v125, 0xba001002, v125
	v_mul_f32_e64 v125, |v100|, v125
	v_mul_f32_e32 v125, 0x3fb8aa3b, v125
	v_exp_f32_e32 v128, v125
	v_mul_f32_e32 v125, v124, v50
	v_mul_f32_e32 v124, v126, v51
	v_or_b32_e32 v51, v99, v101
	v_mul_f32_e32 v50, v128, v53
	v_cvt_f32_i32_e32 v53, v51
	v_mul_f32_e32 v53, 0xba001002, v53
	v_mul_f32_e64 v53, |v100|, v53
	v_mul_f32_e32 v53, 0x3fb8aa3b, v53
	v_exp_f32_e32 v127, v53
	v_or_b32_e32 v53, 1, v51
	v_cvt_f32_i32_e32 v99, v53
	v_mul_f32_e32 v99, 0xba001002, v99
	v_mul_f32_e64 v99, |v100|, v99
	v_mul_f32_e32 v99, 0x3fb8aa3b, v99
	v_exp_f32_e32 v129, v99
	v_or_b32_e32 v99, 2, v51
	v_cvt_f32_i32_e32 v126, v99
	v_mul_f32_e32 v126, 0xba001002, v126
	v_mul_f32_e64 v126, |v100|, v126
	v_mul_f32_e32 v126, 0x3fb8aa3b, v126
	v_exp_f32_e32 v130, v126
	v_or_b32_e32 v126, 3, v51
	v_cvt_f32_i32_e32 v128, v126
	v_mul_f32_e32 v48, v130, v48
	v_mul_f32_e32 v128, 0xba001002, v128
	v_mul_f32_e64 v128, |v100|, v128
	v_mul_f32_e32 v128, 0x3fb8aa3b, v128
	v_exp_f32_e32 v131, v128
	v_mul_f32_e32 v128, v127, v46
	v_mul_f32_e32 v127, v129, v47
	v_or_b32_e32 v47, v93, v101
	v_mul_f32_e32 v46, v131, v49
	v_cvt_f32_i32_e32 v49, v47
	v_mul_f32_e32 v49, 0xba001002, v49
	v_mul_f32_e64 v49, |v100|, v49
	v_mul_f32_e32 v49, 0x3fb8aa3b, v49
	v_exp_f32_e32 v130, v49
	v_or_b32_e32 v49, 1, v47
	v_cvt_f32_i32_e32 v93, v49
	v_mul_f32_e32 v93, 0xba001002, v93
	v_mul_f32_e64 v93, |v100|, v93
	v_mul_f32_e32 v93, 0x3fb8aa3b, v93
	v_exp_f32_e32 v132, v93
	v_or_b32_e32 v93, 2, v47
	v_cvt_f32_i32_e32 v129, v93
	v_mul_f32_e32 v129, 0xba001002, v129
	v_mul_f32_e64 v129, |v100|, v129
	v_mul_f32_e32 v129, 0x3fb8aa3b, v129
	v_exp_f32_e32 v133, v129
	v_or_b32_e32 v129, 3, v47
	v_cvt_f32_i32_e32 v131, v129
	v_mul_f32_e32 v36, v133, v36
	v_mul_f32_e32 v131, 0xba001002, v131
	v_mul_f32_e64 v131, |v100|, v131
	v_mul_f32_e32 v131, 0x3fb8aa3b, v131
	v_exp_f32_e32 v134, v131
	v_mul_f32_e32 v131, v130, v34
	v_mul_f32_e32 v130, v132, v35
	v_or_b32_e32 v35, v90, v101
	v_mul_f32_e32 v34, v134, v37
	v_cvt_f32_i32_e32 v37, v35
	v_mul_f32_e32 v37, 0xba001002, v37
	v_mul_f32_e64 v37, |v100|, v37
	v_mul_f32_e32 v37, 0x3fb8aa3b, v37
	v_exp_f32_e32 v133, v37
	v_or_b32_e32 v37, 1, v35
	v_cvt_f32_i32_e32 v90, v37
	v_mul_f32_e32 v90, 0xba001002, v90
	v_mul_f32_e64 v90, |v100|, v90
	v_mul_f32_e32 v90, 0x3fb8aa3b, v90
	v_exp_f32_e32 v135, v90
	v_or_b32_e32 v90, 2, v35
	v_cvt_f32_i32_e32 v132, v90
	v_mul_f32_e32 v132, 0xba001002, v132
	v_mul_f32_e64 v132, |v100|, v132
	v_mul_f32_e32 v132, 0x3fb8aa3b, v132
	v_exp_f32_e32 v136, v132
	v_or_b32_e32 v132, 3, v35
	v_cvt_f32_i32_e32 v134, v132
	v_mul_f32_e32 v28, v136, v28
	v_mul_f32_e32 v134, 0xba001002, v134
	v_mul_f32_e64 v134, |v100|, v134
	v_mul_f32_e32 v134, 0x3fb8aa3b, v134
	v_exp_f32_e32 v137, v134
	v_mul_f32_e32 v134, v133, v26
	v_or_b32_e32 v26, v89, v101
	v_mul_f32_e32 v133, v135, v27
	v_mul_f32_e32 v27, v137, v29
	v_cvt_f32_i32_e32 v29, v26
	v_mul_f32_e32 v29, 0xba001002, v29
	v_mul_f32_e64 v135, v29, |v100|
	v_or_b32_e32 v29, 1, v26
	v_cvt_f32_i32_e32 v89, v29
	v_mul_f32_e32 v135, 0x3fb8aa3b, v135
	v_exp_f32_e32 v135, v135
	v_mul_f32_e32 v89, 0xba001002, v89
	v_mul_f32_e64 v136, |v100|, v89
	v_or_b32_e32 v89, 2, v26
	v_cvt_f32_i32_e32 v101, v89
	v_mul_f32_e32 v136, 0x3fb8aa3b, v136
	v_exp_f32_e32 v136, v136
	v_mul_f32_e32 v135, v135, v2
	v_mul_f32_e32 v101, 0xba001002, v101
	v_mul_f32_e64 v137, |v100|, v101
	v_or_b32_e32 v101, 3, v26
	v_cvt_f32_i32_e32 v138, v101
	v_mul_f32_e32 v137, 0x3fb8aa3b, v137
	v_exp_f32_e32 v137, v137
	v_mul_f32_e32 v138, 0xba001002, v138
	v_mul_f32_e64 v100, |v100|, v138
	v_mul_f32_e32 v100, 0x3fb8aa3b, v100
	v_exp_f32_e32 v138, v100
	v_mul_f32_e32 v100, v136, v3
	v_mul_f32_e32 v3, v137, v4
	v_add_f32_e64 v4, |v86|, |v96|
	v_add_f32_e64 v4, |v95|, v4
	v_add_f32_e64 v4, |v92|, v4
	v_add_f32_e64 v4, v4, |v85|
	v_add_f32_e64 v4, |v74|, v4
	v_add_f32_e64 v4, |v72|, v4
	v_add_f32_e64 v4, |v71|, v4
	v_add_f32_e64 v4, v4, |v75|
	v_add_f32_e64 v4, |v61|, v4
	v_add_f32_e64 v4, |v59|, v4
	v_add_f32_e64 v4, |v58|, v4
	v_add_f32_e64 v4, v4, |v18|
	v_add_f32_e64 v4, |v103|, v4
	v_add_f32_e64 v4, |v69|, v4
	v_add_f32_e64 v4, |v20|, v4
	v_add_f32_e64 v4, v4, |v56|
	v_add_f32_e64 v4, |v55|, v4
	v_add_f32_e64 v4, |v15|, v4
	v_add_f32_e64 v4, |v64|, v4
	v_add_f32_e64 v4, v4, |v62|
	v_add_f32_e64 v4, |v23|, v4
	v_add_f32_e64 v4, |v106|, v4
	v_add_f32_e64 v4, |v25|, v4
	v_add_f32_e64 v4, v4, |v38|
	v_add_f32_e64 v4, |v110|, v4
	v_add_f32_e64 v4, |v109|, v4
	v_add_f32_e64 v4, |v40|, v4
	v_add_f32_e64 v4, v4, |v113|
	v_add_f32_e64 v4, |v112|, v4
	v_add_f32_e64 v4, |v44|, v4
	v_add_f32_e64 v4, |v42|, v4
	v_add_f32_e64 v4, v4, |v116|
	v_add_f32_e64 v4, |v115|, v4
	v_add_f32_e64 v4, |v31|, v4
	v_add_f32_e64 v4, |v30|, v4
	v_add_f32_e64 v4, v4, |v119|
	v_add_f32_e64 v4, |v118|, v4
	v_add_f32_e64 v4, |v12|, v4
	v_add_f32_e64 v4, |v10|, v4
	v_add_f32_e64 v4, v4, |v122|
	v_add_f32_e64 v4, |v121|, v4
	v_add_f32_e64 v4, |v7|, v4
	v_add_f32_e64 v4, |v6|, v4
	v_add_f32_e64 v4, v4, |v125|
	v_add_f32_e64 v4, |v124|, v4
	v_add_f32_e64 v4, |v52|, v4
	v_add_f32_e64 v4, |v50|, v4
	v_add_f32_e64 v4, v4, |v128|
	v_add_f32_e64 v4, |v127|, v4
	v_add_f32_e64 v4, |v48|, v4
	v_add_f32_e64 v4, |v46|, v4
	v_add_f32_e64 v4, v4, |v131|
	v_add_f32_e64 v4, |v130|, v4
	v_add_f32_e64 v4, |v36|, v4
	v_add_f32_e64 v4, |v34|, v4
	v_add_f32_e64 v4, v4, |v134|
	v_add_f32_e64 v4, |v133|, v4
	v_add_f32_e64 v4, |v28|, v4
	v_add_f32_e64 v4, |v27|, v4
	v_add_f32_e64 v4, v4, |v135|
	v_add_f32_e64 v4, |v100|, v4
	v_mul_f32_e32 v2, v138, v5
	v_add_f32_e64 v4, |v3|, v4
	v_cndmask_b32_e32 v5, v228, v234, vcc
	v_add_f32_e64 v4, |v2|, v4
	v_lshlrev_b32_e32 v5, 2, v5
	ds_bpermute_b32 v5, v5, v4
	v_cmp_lt_i32_e32 vcc, v235, v229
	s_waitcnt lgkmcnt(0)
	v_add_f32_e32 v4, v4, v5
	v_cndmask_b32_e32 v5, v228, v235, vcc
	v_lshlrev_b32_e32 v5, 2, v5
	ds_bpermute_b32 v136, v5, v4
	v_and_b32_e32 v5, 63, v82
	v_cmp_gt_u32_e32 vcc, 16, v5
	s_and_saveexec_b64 s[0:1], vcc
	s_cbranch_execz .LBB0_255
	v_lshlrev_b32_e32 v88, 2, v88
	v_lshlrev_b32_e32 v5, 2, v5
	s_waitcnt lgkmcnt(0)
	v_add_f32_e32 v4, v4, v136
	v_add3_u32 v5, 0, v88, v5
	ds_write_b32 v5, v4 offset:8192
